# q-rope epilogue of the K=256 stream: cos/sin rows of all eight row groups loaded up front, counted vmcnt waits
# baseline (speedup 1.0000x reference)
; __device__ __forceinline__ unsigned pk2(float lo, float hi) { f32x2_t v = {lo, hi}; bf16x2_t b = __builtin_convertvector(v, bf16x2_t); return __builtin_bit_cast(unsigned, b); }
;     __device__ __forceinline__ void operator()(const f32x4 (&acc)[2][2][4][2], const Unit& u, int wr, int wc, int fr, int fq) const {
;     ...
;                 for (int m = 0; m < 4; ++m) { const int row = row0 + ai * HALF + m * 16; const float* rp = rope + posidx(row) * 32 + 4 * fq; bf16_t* qp = Q + (size_t)row * QW;
; #pragma unroll
;                     for (int bj = 0; bj < 2; ++bj) { const int col32 = u.pn * BM + bj * HALF + wc * 32; f32x4 v0 = acc[ai][bj][m][0], v1 = acc[ai][bj][m][1];
;                         if ((col32 % 96) == 64) { const f32x4 c = *(const f32x4*)rp, s = *(const f32x4*)(rp + 16); const f32x4 o0 = v0 * c - v1 * s, o1 = v1 * c + v0 * s; v0 = o0; v1 = o1; }
;                         v0 = v0 * QSCALE; v1 = v1 * QSCALE;
;                         u32x2 w0, w1; w0.x = pk2(v0[0], v0[1]); w0.y = pk2(v0[2], v0[3]); w1.x = pk2(v1[0], v1[1]); w1.y = pk2(v1[2], v1[3]);
;                         *(u32x2*)(qp + col32 + 4 * fq) = w0; *(u32x2*)(qp + col32 + 16 + 4 * fq) = w1; } }
.LBB0_911:
	s_and_b64 vcc, exec, s[12:13]
	s_cbranch_vccz .LBB0_945
	s_lshl_b32 s12, s48, 8
	v_readlane_b32 s13, v237, 18
	s_or_b32 s94, s12, s13
	s_mul_hi_i32 s12, s94, 0x2aaaaaab
	v_and_or_b32 v145, v130, 7, v167
	v_and_b32_e32 v130, 0x7cf, v158
	v_cmp_gt_i32_e32 vcc, s34, v158
	s_lshr_b32 s13, s12, 31
	s_lshr_b32 s12, s12, 4
	v_cndmask_b32_e32 v130, v145, v130, vcc
	s_add_i32 s12, s12, s13
	v_lshlrev_b32_e32 v138, 2, v144
	v_lshlrev_b32_e32 v150, 7, v130
	s_mulk_i32 s12, 0x60
	v_ashrrev_i32_e32 v139, 31, v138
	v_lshl_add_u64 v[130:131], s[68:69], 0, v[150:151]
	s_sub_i32 s12, s94, s12
	v_lshl_add_u64 v[140:141], v[138:139], 2, v[130:131]
	s_or_b32 s83, s94, 0x80
	s_mul_hi_i32 s85, s83, 0x2aaaaaab
	s_lshr_b32 s13, s85, 31
	s_lshr_b32 s85, s85, 4
	s_add_i32 s85, s85, s13
	s_mulk_i32 s85, 0x60
	s_sub_i32 s83, s83, s85
	s_cmp_eq_u32 s12, 64
	s_cbranch_scc1 .Lrope_b1
	s_cmp_eq_u32 s83, 64
	s_cbranch_scc0 .Lrope_b1_done
.Lrope_b1:
	v_add_u32_e32 v132, 0, v158
	v_and_b32_e32 v133, 0x7ff, v132
	v_cmp_gt_i32_e32 vcc, s34, v132
	s_nop 1
	v_cndmask_b32_e32 v133, v145, v133, vcc
	v_lshlrev_b32_e32 v150, 7, v133
	v_lshl_add_u64 v[134:135], s[68:69], 0, v[150:151]
	v_lshl_add_u64 v[134:135], v[138:139], 2, v[134:135]
	global_load_dwordx4 v[174:177], v[134:135], off offset:64
	global_load_dwordx4 v[178:181], v[134:135], off
	v_add_u32_e32 v132, 16, v158
	v_and_b32_e32 v133, 0x7ff, v132
	v_cmp_gt_i32_e32 vcc, s34, v132
	s_nop 1
	v_cndmask_b32_e32 v133, v145, v133, vcc
	v_lshlrev_b32_e32 v150, 7, v133
	v_lshl_add_u64 v[134:135], s[68:69], 0, v[150:151]
	v_lshl_add_u64 v[134:135], v[138:139], 2, v[134:135]
	global_load_dwordx4 v[182:185], v[134:135], off offset:64
	global_load_dwordx4 v[186:189], v[134:135], off
	v_add_u32_e32 v132, 32, v158
	v_and_b32_e32 v133, 0x7ff, v132
	v_cmp_gt_i32_e32 vcc, s34, v132
	s_nop 1
	v_cndmask_b32_e32 v133, v145, v133, vcc
	v_lshlrev_b32_e32 v150, 7, v133
	v_lshl_add_u64 v[134:135], s[68:69], 0, v[150:151]
	v_lshl_add_u64 v[134:135], v[138:139], 2, v[134:135]
	global_load_dwordx4 v[190:193], v[134:135], off offset:64
	global_load_dwordx4 v[194:197], v[134:135], off
	v_add_u32_e32 v132, 48, v158
	v_and_b32_e32 v133, 0x7ff, v132
	v_cmp_gt_i32_e32 vcc, s34, v132
	s_nop 1
	v_cndmask_b32_e32 v133, v145, v133, vcc
	v_lshlrev_b32_e32 v150, 7, v133
	v_lshl_add_u64 v[134:135], s[68:69], 0, v[150:151]
	v_lshl_add_u64 v[134:135], v[138:139], 2, v[134:135]
	global_load_dwordx4 v[198:201], v[134:135], off offset:64
	global_load_dwordx4 v[202:205], v[134:135], off
	v_add_u32_e32 v132, 0x80, v158
	v_and_b32_e32 v133, 0x7ff, v132
	v_cmp_gt_i32_e32 vcc, s34, v132
	s_nop 1
	v_cndmask_b32_e32 v133, v145, v133, vcc
	v_lshlrev_b32_e32 v150, 7, v133
	v_lshl_add_u64 v[134:135], s[68:69], 0, v[150:151]
	v_lshl_add_u64 v[134:135], v[138:139], 2, v[134:135]
	global_load_dwordx4 v[206:209], v[134:135], off offset:64
	global_load_dwordx4 v[210:213], v[134:135], off
	v_add_u32_e32 v132, 0x90, v158
	v_and_b32_e32 v133, 0x7ff, v132
	v_cmp_gt_i32_e32 vcc, s34, v132
	s_nop 1
	v_cndmask_b32_e32 v133, v145, v133, vcc
	v_lshlrev_b32_e32 v150, 7, v133
	v_lshl_add_u64 v[134:135], s[68:69], 0, v[150:151]
	v_lshl_add_u64 v[134:135], v[138:139], 2, v[134:135]
	global_load_dwordx4 v[214:217], v[134:135], off offset:64
	global_load_dwordx4 v[218:221], v[134:135], off
.Lrope_b1_done:
	s_cmp_eq_u32 s12, 64
	v_mov_b64_e32 v[132:133], v[124:125]
	v_mov_b64_e32 v[136:137], v[128:129]
	s_cselect_b64 s[14:15], -1, 0
	s_cmp_lg_u32 s12, 64
	v_mov_b64_e32 v[130:131], v[122:123]
	v_mov_b64_e32 v[134:135], v[126:127]
	s_cbranch_scc1 .LBB0_914
	s_waitcnt vmcnt(10)
	v_pk_mul_f32 v[134:135], v[124:125], v[176:177]
	v_pk_mul_f32 v[142:143], v[122:123], v[174:175]
	v_pk_mul_f32 v[132:133], v[128:129], v[176:177]
	v_pk_mul_f32 v[130:131], v[126:127], v[174:175]
	v_pk_fma_f32 v[136:137], v[128:129], v[180:181], v[134:135] neg_lo:[0,0,1] neg_hi:[0,0,1]
	v_pk_fma_f32 v[134:135], v[126:127], v[178:179], v[142:143] neg_lo:[0,0,1] neg_hi:[0,0,1]
	v_pk_fma_f32 v[132:133], v[124:125], v[180:181], v[132:133]
	v_pk_fma_f32 v[130:131], v[122:123], v[178:179], v[130:131]
.LBB0_914:
	v_mov_b64_e32 v[142:143], s[66:67]
	v_mad_i64_i32 v[142:143], s[12:13], v158, s41, v[142:143]
	s_or_b32 s12, s94, 0x80
	s_mul_hi_i32 s13, s12, 0x2aaaaaab
	s_lshr_b32 s24, s13, 31
	s_lshr_b32 s13, s13, 4
	v_pk_mul_f32 v[132:133], v[132:133], s[80:81] op_sel_hi:[1,0]
	v_pk_mul_f32 v[130:131], v[130:131], s[80:81] op_sel_hi:[1,0]
	s_ashr_i32 s95, s94, 31
	s_add_i32 s13, s13, s24
	v_pk_mul_f32 v[136:137], v[136:137], s[80:81] op_sel_hi:[1,0]
	v_pk_mul_f32 v[134:135], v[134:135], s[80:81] op_sel_hi:[1,0]
	v_cvt_pk_bf16_f32 v130, v130, v131
	v_cvt_pk_bf16_f32 v131, v132, v133
	v_lshl_add_u64 v[132:133], s[94:95], 1, v[142:143]
	s_mulk_i32 s13, 0x60
	v_cvt_pk_bf16_f32 v134, v134, v135
	v_cvt_pk_bf16_f32 v135, v136, v137
	v_lshl_add_u64 v[142:143], v[138:139], 1, v[132:133]
	s_sub_i32 s12, s12, s13
	v_mov_b32_e32 v240, v134
	v_mov_b32_e32 v241, v135
	v_mov_b32_e32 v242, v130
	v_mov_b32_e32 v243, v131
	s_nop 1
	v_permlane16_swap_b32_e32 v240, v242
	v_permlane16_swap_b32_e32 v241, v243
	v_lshl_add_u64 v[238:239], v[142:143], 0, v[248:249]
	global_store_dwordx4 v[238:239], v[240:243], off
	s_cmp_eq_u32 s12, 64
	v_mov_b64_e32 v[132:133], v[92:93]
	v_mov_b64_e32 v[136:137], v[96:97]
	s_cselect_b64 s[96:97], -1, 0
	s_cmp_lg_u32 s12, 64
	v_mov_b64_e32 v[130:131], v[90:91]
	v_mov_b64_e32 v[134:135], v[94:95]
	s_cbranch_scc1 .LBB0_916
	s_waitcnt vmcnt(11)
	v_pk_mul_f32 v[134:135], v[92:93], v[176:177]
	v_pk_mul_f32 v[140:141], v[90:91], v[174:175]
	v_pk_mul_f32 v[132:133], v[96:97], v[176:177]
	v_pk_mul_f32 v[130:131], v[94:95], v[174:175]
	v_pk_fma_f32 v[136:137], v[96:97], v[180:181], v[134:135] neg_lo:[0,0,1] neg_hi:[0,0,1]
	v_pk_fma_f32 v[134:135], v[94:95], v[178:179], v[140:141] neg_lo:[0,0,1] neg_hi:[0,0,1]
	v_pk_fma_f32 v[132:133], v[92:93], v[180:181], v[132:133]
	v_pk_fma_f32 v[130:131], v[90:91], v[178:179], v[130:131]
; __device__ __forceinline__ unsigned pk2(float lo, float hi) { f32x2_t v = {lo, hi}; bf16x2_t b = __builtin_convertvector(v, bf16x2_t); return __builtin_bit_cast(unsigned, b); }
;     __device__ __forceinline__ void operator()(const f32x4 (&acc)[2][2][4][2], const Unit& u, int wr, int wc, int fr, int fq) const {
;     ...
;                 for (int m = 0; m < 4; ++m) { const int row = row0 + ai * HALF + m * 16; const float* rp = rope + posidx(row) * 32 + 4 * fq; bf16_t* qp = Q + (size_t)row * QW;
; #pragma unroll
;                     for (int bj = 0; bj < 2; ++bj) { const int col32 = u.pn * BM + bj * HALF + wc * 32; f32x4 v0 = acc[ai][bj][m][0], v1 = acc[ai][bj][m][1];
;                         if ((col32 % 96) == 64) { const f32x4 c = *(const f32x4*)rp, s = *(const f32x4*)(rp + 16); const f32x4 o0 = v0 * c - v1 * s, o1 = v1 * c + v0 * s; v0 = o0; v1 = o1; }
;                         v0 = v0 * QSCALE; v1 = v1 * QSCALE;
;                         u32x2 w0, w1; w0.x = pk2(v0[0], v0[1]); w0.y = pk2(v0[2], v0[3]); w1.x = pk2(v1[0], v1[1]); w1.y = pk2(v1[2], v1[3]);
;                         *(u32x2*)(qp + col32 + 4 * fq) = w0; *(u32x2*)(qp + col32 + 16 + 4 * fq) = w1; } }
.LBB0_916:
	v_pk_mul_f32 v[136:137], v[136:137], s[80:81] op_sel_hi:[1,0]
	v_pk_mul_f32 v[134:135], v[134:135], s[80:81] op_sel_hi:[1,0]
	v_pk_mul_f32 v[132:133], v[132:133], s[80:81] op_sel_hi:[1,0]
	v_pk_mul_f32 v[130:131], v[130:131], s[80:81] op_sel_hi:[1,0]
	v_cvt_pk_bf16_f32 v134, v134, v135
	v_cvt_pk_bf16_f32 v135, v136, v137
	v_cvt_pk_bf16_f32 v130, v130, v131
	v_cvt_pk_bf16_f32 v131, v132, v133
	v_mov_b32_e32 v244, v134
	v_mov_b32_e32 v245, v135
	v_mov_b32_e32 v246, v130
	v_mov_b32_e32 v247, v131
	s_nop 1
	v_permlane16_swap_b32_e32 v244, v246
	v_permlane16_swap_b32_e32 v245, v247
	v_lshl_add_u64 v[234:235], v[142:143], 0, v[248:249]
	global_store_dwordx4 v[234:235], v[244:247], off offset:256
	s_or_b64 vcc, s[14:15], s[96:97]
	s_cbranch_scc0 .Lrope_b2_done
	v_add_u32_e32 v132, 0xa0, v158
	v_and_b32_e32 v133, 0x7ff, v132
	v_cmp_gt_i32_e32 vcc, s34, v132
	s_nop 1
	v_cndmask_b32_e32 v133, v145, v133, vcc
	v_lshlrev_b32_e32 v150, 7, v133
	v_lshl_add_u64 v[134:135], s[68:69], 0, v[150:151]
	v_lshl_add_u64 v[134:135], v[138:139], 2, v[134:135]
	global_load_dwordx4 v[122:125], v[134:135], off offset:64
	global_load_dwordx4 v[126:129], v[134:135], off
	v_add_u32_e32 v132, 0xb0, v158
	v_and_b32_e32 v133, 0x7ff, v132
	v_cmp_gt_i32_e32 vcc, s34, v132
	s_nop 1
	v_cndmask_b32_e32 v133, v145, v133, vcc
	v_lshlrev_b32_e32 v150, 7, v133
	v_lshl_add_u64 v[134:135], s[68:69], 0, v[150:151]
	v_lshl_add_u64 v[134:135], v[138:139], 2, v[134:135]
	global_load_dwordx4 v[90:93], v[134:135], off offset:64
	global_load_dwordx4 v[94:97], v[134:135], off
.Lrope_b2_done:
	v_or_b32_e32 v142, 16, v158
	s_movk_i32 s12, 0x7df
	v_bitop3_b32 v130, v158, s12, 16 bitop3:0xc8
	v_cmp_gt_i32_e32 vcc, s34, v142
	v_mov_b64_e32 v[136:137], v[120:121]
	v_mov_b64_e32 v[134:135], v[118:119]
	v_cndmask_b32_e32 v130, v145, v130, vcc
	v_lshlrev_b32_e32 v150, 7, v130
	v_lshl_add_u64 v[130:131], s[68:69], 0, v[150:151]
	v_lshl_add_u64 v[140:141], v[138:139], 2, v[130:131]
	v_cndmask_b32_e64 v130, 0, 1, s[14:15]
	v_cmp_ne_u32_e64 s[12:13], 1, v130
	v_mov_b64_e32 v[132:133], v[116:117]
	s_andn2_b64 vcc, exec, s[14:15]
	v_mov_b64_e32 v[130:131], v[114:115]
	s_cbranch_vccnz .LBB0_918
	s_waitcnt vmcnt(14)
	v_pk_mul_f32 v[134:135], v[116:117], v[184:185]
	v_pk_mul_f32 v[170:171], v[114:115], v[182:183]
	v_pk_mul_f32 v[132:133], v[120:121], v[184:185]
	v_pk_mul_f32 v[130:131], v[118:119], v[182:183]
	v_pk_fma_f32 v[136:137], v[120:121], v[188:189], v[134:135] neg_lo:[0,0,1] neg_hi:[0,0,1]
	v_pk_fma_f32 v[134:135], v[118:119], v[186:187], v[170:171] neg_lo:[0,0,1] neg_hi:[0,0,1]
	v_pk_fma_f32 v[132:133], v[116:117], v[188:189], v[132:133]
	v_pk_fma_f32 v[130:131], v[114:115], v[186:187], v[130:131]
.LBB0_918:
	v_mov_b64_e32 v[160:161], s[66:67]
	v_mad_i64_i32 v[142:143], s[14:15], v142, s41, v[160:161]
	v_pk_mul_f32 v[132:133], v[132:133], s[80:81] op_sel_hi:[1,0]
	v_pk_mul_f32 v[130:131], v[130:131], s[80:81] op_sel_hi:[1,0]
	v_pk_mul_f32 v[136:137], v[136:137], s[80:81] op_sel_hi:[1,0]
	v_pk_mul_f32 v[134:135], v[134:135], s[80:81] op_sel_hi:[1,0]
	v_cvt_pk_bf16_f32 v130, v130, v131
	v_cvt_pk_bf16_f32 v131, v132, v133
	v_lshl_add_u64 v[132:133], s[94:95], 1, v[142:143]
	v_cvt_pk_bf16_f32 v134, v134, v135
	v_cvt_pk_bf16_f32 v135, v136, v137
	v_lshl_add_u64 v[142:143], v[138:139], 1, v[132:133]
	v_mov_b32_e32 v226, v134
	v_mov_b32_e32 v227, v135
	v_mov_b32_e32 v228, v130
	v_mov_b32_e32 v229, v131
	s_nop 1
	v_permlane16_swap_b32_e32 v226, v228
	v_permlane16_swap_b32_e32 v227, v229
	v_lshl_add_u64 v[224:225], v[142:143], 0, v[248:249]
	global_store_dwordx4 v[224:225], v[226:229], off
	v_cndmask_b32_e64 v130, 0, 1, s[96:97]
	v_cmp_ne_u32_e64 s[14:15], 1, v130
	v_mov_b64_e32 v[132:133], v[84:85]
	v_mov_b64_e32 v[136:137], v[88:89]
	s_andn2_b64 vcc, exec, s[96:97]
	v_mov_b64_e32 v[130:131], v[82:83]
	v_mov_b64_e32 v[134:135], v[86:87]
	s_cbranch_vccnz .LBB0_920
	s_waitcnt vmcnt(15)
	v_pk_mul_f32 v[134:135], v[84:85], v[184:185]
	v_pk_mul_f32 v[140:141], v[82:83], v[182:183]
	v_pk_mul_f32 v[132:133], v[88:89], v[184:185]
	v_pk_mul_f32 v[130:131], v[86:87], v[182:183]
	v_pk_fma_f32 v[136:137], v[88:89], v[188:189], v[134:135] neg_lo:[0,0,1] neg_hi:[0,0,1]
	v_pk_fma_f32 v[134:135], v[86:87], v[186:187], v[140:141] neg_lo:[0,0,1] neg_hi:[0,0,1]
	v_pk_fma_f32 v[132:133], v[84:85], v[188:189], v[132:133]
	v_pk_fma_f32 v[130:131], v[82:83], v[186:187], v[130:131]
.LBB0_920:
	v_pk_mul_f32 v[136:137], v[136:137], s[80:81] op_sel_hi:[1,0]
	v_pk_mul_f32 v[134:135], v[134:135], s[80:81] op_sel_hi:[1,0]
	v_pk_mul_f32 v[132:133], v[132:133], s[80:81] op_sel_hi:[1,0]
	v_pk_mul_f32 v[130:131], v[130:131], s[80:81] op_sel_hi:[1,0]
	v_cvt_pk_bf16_f32 v134, v134, v135
	v_cvt_pk_bf16_f32 v135, v136, v137
	v_cvt_pk_bf16_f32 v130, v130, v131
	v_cvt_pk_bf16_f32 v131, v132, v133
	v_mov_b32_e32 v230, v134
	v_mov_b32_e32 v231, v135
	v_mov_b32_e32 v232, v130
	v_mov_b32_e32 v233, v131
	s_nop 1
	v_permlane16_swap_b32_e32 v230, v232
	v_permlane16_swap_b32_e32 v231, v233
	v_lshl_add_u64 v[222:223], v[142:143], 0, v[248:249]
	global_store_dwordx4 v[222:223], v[230:233], off offset:256
	v_or_b32_e32 v142, 32, v158
	s_movk_i32 s24, 0x7ef
	v_bitop3_b32 v130, v158, s24, 32 bitop3:0xc8
	v_cmp_gt_i32_e32 vcc, s34, v142
	v_mov_b64_e32 v[136:137], v[112:113]
	v_mov_b64_e32 v[134:135], v[110:111]
	v_cndmask_b32_e32 v130, v145, v130, vcc
	v_lshlrev_b32_e32 v150, 7, v130
	v_lshl_add_u64 v[130:131], s[68:69], 0, v[150:151]
	v_lshl_add_u64 v[140:141], v[138:139], 2, v[130:131]
	v_mov_b64_e32 v[132:133], v[108:109]
	s_and_b64 vcc, exec, s[12:13]
	v_mov_b64_e32 v[130:131], v[106:107]
	s_cbranch_vccnz .LBB0_922
	s_waitcnt vmcnt(14)
	v_pk_mul_f32 v[134:135], v[108:109], v[192:193]
	v_pk_mul_f32 v[170:171], v[106:107], v[190:191]
	v_pk_mul_f32 v[132:133], v[112:113], v[192:193]
	v_pk_mul_f32 v[130:131], v[110:111], v[190:191]
	v_pk_fma_f32 v[136:137], v[112:113], v[196:197], v[134:135] neg_lo:[0,0,1] neg_hi:[0,0,1]
	v_pk_fma_f32 v[134:135], v[110:111], v[194:195], v[170:171] neg_lo:[0,0,1] neg_hi:[0,0,1]
	v_pk_fma_f32 v[132:133], v[108:109], v[196:197], v[132:133]
	v_pk_fma_f32 v[130:131], v[106:107], v[194:195], v[130:131]
; __device__ __forceinline__ unsigned pk2(float lo, float hi) { f32x2_t v = {lo, hi}; bf16x2_t b = __builtin_convertvector(v, bf16x2_t); return __builtin_bit_cast(unsigned, b); }
;     __device__ __forceinline__ void operator()(const f32x4 (&acc)[2][2][4][2], const Unit& u, int wr, int wc, int fr, int fq) const {
;     ...
;                 for (int m = 0; m < 4; ++m) { const int row = row0 + ai * HALF + m * 16; const float* rp = rope + posidx(row) * 32 + 4 * fq; bf16_t* qp = Q + (size_t)row * QW;
; #pragma unroll
;                     for (int bj = 0; bj < 2; ++bj) { const int col32 = u.pn * BM + bj * HALF + wc * 32; f32x4 v0 = acc[ai][bj][m][0], v1 = acc[ai][bj][m][1];
;                         if ((col32 % 96) == 64) { const f32x4 c = *(const f32x4*)rp, s = *(const f32x4*)(rp + 16); const f32x4 o0 = v0 * c - v1 * s, o1 = v1 * c + v0 * s; v0 = o0; v1 = o1; }
;                         v0 = v0 * QSCALE; v1 = v1 * QSCALE;
;                         u32x2 w0, w1; w0.x = pk2(v0[0], v0[1]); w0.y = pk2(v0[2], v0[3]); w1.x = pk2(v1[0], v1[1]); w1.y = pk2(v1[2], v1[3]);
;                         *(u32x2*)(qp + col32 + 4 * fq) = w0; *(u32x2*)(qp + col32 + 16 + 4 * fq) = w1; } }
.LBB0_922:
	v_mov_b64_e32 v[160:161], s[66:67]
	v_mad_i64_i32 v[142:143], s[24:25], v142, s41, v[160:161]
	v_pk_mul_f32 v[132:133], v[132:133], s[80:81] op_sel_hi:[1,0]
	v_pk_mul_f32 v[130:131], v[130:131], s[80:81] op_sel_hi:[1,0]
	v_pk_mul_f32 v[136:137], v[136:137], s[80:81] op_sel_hi:[1,0]
	v_pk_mul_f32 v[134:135], v[134:135], s[80:81] op_sel_hi:[1,0]
	v_cvt_pk_bf16_f32 v130, v130, v131
	v_cvt_pk_bf16_f32 v131, v132, v133
	v_lshl_add_u64 v[132:133], s[94:95], 1, v[142:143]
	v_cvt_pk_bf16_f32 v134, v134, v135
	v_cvt_pk_bf16_f32 v135, v136, v137
	v_lshl_add_u64 v[142:143], v[138:139], 1, v[132:133]
	v_mov_b32_e32 v240, v134
	v_mov_b32_e32 v241, v135
	v_mov_b32_e32 v242, v130
	v_mov_b32_e32 v243, v131
	s_nop 1
	v_permlane16_swap_b32_e32 v240, v242
	v_permlane16_swap_b32_e32 v241, v243
	v_lshl_add_u64 v[238:239], v[142:143], 0, v[248:249]
	global_store_dwordx4 v[238:239], v[240:243], off
	v_mov_b64_e32 v[132:133], v[76:77]
	v_mov_b64_e32 v[136:137], v[80:81]
	s_and_b64 vcc, exec, s[14:15]
	v_mov_b64_e32 v[130:131], v[74:75]
	v_mov_b64_e32 v[134:135], v[78:79]
	s_cbranch_vccnz .LBB0_924
	s_waitcnt vmcnt(15)
	v_pk_mul_f32 v[134:135], v[76:77], v[192:193]
	v_pk_mul_f32 v[140:141], v[74:75], v[190:191]
	v_pk_mul_f32 v[132:133], v[80:81], v[192:193]
	v_pk_mul_f32 v[130:131], v[78:79], v[190:191]
	v_pk_fma_f32 v[136:137], v[80:81], v[196:197], v[134:135] neg_lo:[0,0,1] neg_hi:[0,0,1]
	v_pk_fma_f32 v[134:135], v[78:79], v[194:195], v[140:141] neg_lo:[0,0,1] neg_hi:[0,0,1]
	v_pk_fma_f32 v[132:133], v[76:77], v[196:197], v[132:133]
	v_pk_fma_f32 v[130:131], v[74:75], v[194:195], v[130:131]
.LBB0_924:
	v_pk_mul_f32 v[136:137], v[136:137], s[80:81] op_sel_hi:[1,0]
	v_pk_mul_f32 v[134:135], v[134:135], s[80:81] op_sel_hi:[1,0]
	v_pk_mul_f32 v[132:133], v[132:133], s[80:81] op_sel_hi:[1,0]
	v_pk_mul_f32 v[130:131], v[130:131], s[80:81] op_sel_hi:[1,0]
	v_cvt_pk_bf16_f32 v134, v134, v135
	v_cvt_pk_bf16_f32 v135, v136, v137
	v_cvt_pk_bf16_f32 v130, v130, v131
	v_cvt_pk_bf16_f32 v131, v132, v133
	v_mov_b32_e32 v244, v134
	v_mov_b32_e32 v245, v135
	v_mov_b32_e32 v246, v130
	v_mov_b32_e32 v247, v131
	s_nop 1
	v_permlane16_swap_b32_e32 v244, v246
	v_permlane16_swap_b32_e32 v245, v247
	v_lshl_add_u64 v[234:235], v[142:143], 0, v[248:249]
	global_store_dwordx4 v[234:235], v[244:247], off offset:256
	v_or_b32_e32 v142, 48, v158
	s_movk_i32 s24, 0x7ff
	v_bitop3_b32 v130, v158, s24, 48 bitop3:0xc8
	v_cmp_gt_i32_e32 vcc, s34, v142
	v_mov_b64_e32 v[136:137], v[104:105]
	v_mov_b64_e32 v[134:135], v[102:103]
	v_cndmask_b32_e32 v130, v145, v130, vcc
	v_lshlrev_b32_e32 v150, 7, v130
	v_lshl_add_u64 v[130:131], s[68:69], 0, v[150:151]
	v_lshl_add_u64 v[140:141], v[138:139], 2, v[130:131]
	v_mov_b64_e32 v[132:133], v[100:101]
	s_and_b64 vcc, exec, s[12:13]
	v_mov_b64_e32 v[130:131], v[98:99]
	s_cbranch_vccnz .LBB0_926
	s_waitcnt vmcnt(14)
	v_pk_mul_f32 v[134:135], v[100:101], v[200:201]
	v_pk_mul_f32 v[170:171], v[98:99], v[198:199]
	v_pk_mul_f32 v[132:133], v[104:105], v[200:201]
	v_pk_mul_f32 v[130:131], v[102:103], v[198:199]
	v_pk_fma_f32 v[136:137], v[104:105], v[204:205], v[134:135] neg_lo:[0,0,1] neg_hi:[0,0,1]
	v_pk_fma_f32 v[134:135], v[102:103], v[202:203], v[170:171] neg_lo:[0,0,1] neg_hi:[0,0,1]
	v_pk_fma_f32 v[132:133], v[100:101], v[204:205], v[132:133]
	v_pk_fma_f32 v[130:131], v[98:99], v[202:203], v[130:131]
.LBB0_926:
	v_mov_b64_e32 v[160:161], s[66:67]
	v_mad_i64_i32 v[142:143], s[24:25], v142, s41, v[160:161]
	v_pk_mul_f32 v[132:133], v[132:133], s[80:81] op_sel_hi:[1,0]
	v_pk_mul_f32 v[130:131], v[130:131], s[80:81] op_sel_hi:[1,0]
	v_pk_mul_f32 v[136:137], v[136:137], s[80:81] op_sel_hi:[1,0]
	v_pk_mul_f32 v[134:135], v[134:135], s[80:81] op_sel_hi:[1,0]
	v_cvt_pk_bf16_f32 v130, v130, v131
	v_cvt_pk_bf16_f32 v131, v132, v133
	v_lshl_add_u64 v[132:133], s[94:95], 1, v[142:143]
	v_cvt_pk_bf16_f32 v134, v134, v135
	v_cvt_pk_bf16_f32 v135, v136, v137
	v_lshl_add_u64 v[142:143], v[138:139], 1, v[132:133]
	v_mov_b32_e32 v226, v134
	v_mov_b32_e32 v227, v135
	v_mov_b32_e32 v228, v130
	v_mov_b32_e32 v229, v131
	s_nop 1
	v_permlane16_swap_b32_e32 v226, v228
	v_permlane16_swap_b32_e32 v227, v229
	v_lshl_add_u64 v[224:225], v[142:143], 0, v[248:249]
	global_store_dwordx4 v[224:225], v[226:229], off
	v_mov_b64_e32 v[132:133], v[68:69]
	v_mov_b64_e32 v[136:137], v[72:73]
	s_and_b64 vcc, exec, s[14:15]
	v_mov_b64_e32 v[130:131], v[66:67]
	v_mov_b64_e32 v[134:135], v[70:71]
	s_cbranch_vccnz .LBB0_928
	s_waitcnt vmcnt(15)
	v_pk_mul_f32 v[134:135], v[68:69], v[200:201]
	v_pk_mul_f32 v[140:141], v[66:67], v[198:199]
	v_pk_mul_f32 v[132:133], v[72:73], v[200:201]
	v_pk_mul_f32 v[130:131], v[70:71], v[198:199]
	v_pk_fma_f32 v[136:137], v[72:73], v[204:205], v[134:135] neg_lo:[0,0,1] neg_hi:[0,0,1]
	v_pk_fma_f32 v[134:135], v[70:71], v[202:203], v[140:141] neg_lo:[0,0,1] neg_hi:[0,0,1]
	v_pk_fma_f32 v[132:133], v[68:69], v[204:205], v[132:133]
	v_pk_fma_f32 v[130:131], v[66:67], v[202:203], v[130:131]
; __device__ __forceinline__ unsigned pk2(float lo, float hi) { f32x2_t v = {lo, hi}; bf16x2_t b = __builtin_convertvector(v, bf16x2_t); return __builtin_bit_cast(unsigned, b); }
;     __device__ __forceinline__ void operator()(const f32x4 (&acc)[2][2][4][2], const Unit& u, int wr, int wc, int fr, int fq) const {
;     ...
;                 for (int m = 0; m < 4; ++m) { const int row = row0 + ai * HALF + m * 16; const float* rp = rope + posidx(row) * 32 + 4 * fq; bf16_t* qp = Q + (size_t)row * QW;
; #pragma unroll
;                     for (int bj = 0; bj < 2; ++bj) { const int col32 = u.pn * BM + bj * HALF + wc * 32; f32x4 v0 = acc[ai][bj][m][0], v1 = acc[ai][bj][m][1];
;                         if ((col32 % 96) == 64) { const f32x4 c = *(const f32x4*)rp, s = *(const f32x4*)(rp + 16); const f32x4 o0 = v0 * c - v1 * s, o1 = v1 * c + v0 * s; v0 = o0; v1 = o1; }
;                         v0 = v0 * QSCALE; v1 = v1 * QSCALE;
;                         u32x2 w0, w1; w0.x = pk2(v0[0], v0[1]); w0.y = pk2(v0[2], v0[3]); w1.x = pk2(v1[0], v1[1]); w1.y = pk2(v1[2], v1[3]);
;                         *(u32x2*)(qp + col32 + 4 * fq) = w0; *(u32x2*)(qp + col32 + 16 + 4 * fq) = w1; } }
.LBB0_928:
	v_pk_mul_f32 v[136:137], v[136:137], s[80:81] op_sel_hi:[1,0]
	v_pk_mul_f32 v[134:135], v[134:135], s[80:81] op_sel_hi:[1,0]
	v_pk_mul_f32 v[132:133], v[132:133], s[80:81] op_sel_hi:[1,0]
	v_pk_mul_f32 v[130:131], v[130:131], s[80:81] op_sel_hi:[1,0]
	v_cvt_pk_bf16_f32 v134, v134, v135
	v_cvt_pk_bf16_f32 v135, v136, v137
	v_cvt_pk_bf16_f32 v130, v130, v131
	v_cvt_pk_bf16_f32 v131, v132, v133
	v_mov_b32_e32 v230, v134
	v_mov_b32_e32 v231, v135
	v_mov_b32_e32 v232, v130
	v_mov_b32_e32 v233, v131
	s_nop 1
	v_permlane16_swap_b32_e32 v230, v232
	v_permlane16_swap_b32_e32 v231, v233
	v_lshl_add_u64 v[222:223], v[142:143], 0, v[248:249]
	global_store_dwordx4 v[222:223], v[230:233], off offset:256
	v_add_u32_e32 v142, 0x80, v158
	s_movk_i32 s24, 0x7f80
	v_and_b32_e32 v130, 0x7cf, v142
	v_cmp_gt_i32_e32 vcc, s24, v158
	v_mov_b64_e32 v[136:137], v[64:65]
	v_mov_b64_e32 v[134:135], v[62:63]
	v_cndmask_b32_e32 v130, v145, v130, vcc
	v_lshlrev_b32_e32 v150, 7, v130
	v_lshl_add_u64 v[130:131], s[68:69], 0, v[150:151]
	v_lshl_add_u64 v[140:141], v[138:139], 2, v[130:131]
	v_mov_b64_e32 v[132:133], v[60:61]
	s_and_b64 vcc, exec, s[12:13]
	v_mov_b64_e32 v[130:131], v[58:59]
	s_cbranch_vccnz .LBB0_930
	s_waitcnt vmcnt(14)
	v_pk_mul_f32 v[134:135], v[60:61], v[208:209]
	v_pk_mul_f32 v[170:171], v[58:59], v[206:207]
	v_pk_mul_f32 v[132:133], v[64:65], v[208:209]
	v_pk_mul_f32 v[130:131], v[62:63], v[206:207]
	v_pk_fma_f32 v[136:137], v[64:65], v[212:213], v[134:135] neg_lo:[0,0,1] neg_hi:[0,0,1]
	v_pk_fma_f32 v[134:135], v[62:63], v[210:211], v[170:171] neg_lo:[0,0,1] neg_hi:[0,0,1]
	v_pk_fma_f32 v[132:133], v[60:61], v[212:213], v[132:133]
	v_pk_fma_f32 v[130:131], v[58:59], v[210:211], v[130:131]
.LBB0_930:
	v_mov_b64_e32 v[160:161], s[66:67]
	v_mad_i64_i32 v[142:143], s[24:25], v142, s41, v[160:161]
	v_pk_mul_f32 v[132:133], v[132:133], s[80:81] op_sel_hi:[1,0]
	v_pk_mul_f32 v[130:131], v[130:131], s[80:81] op_sel_hi:[1,0]
	v_pk_mul_f32 v[136:137], v[136:137], s[80:81] op_sel_hi:[1,0]
	v_pk_mul_f32 v[134:135], v[134:135], s[80:81] op_sel_hi:[1,0]
	v_cvt_pk_bf16_f32 v130, v130, v131
	v_cvt_pk_bf16_f32 v131, v132, v133
	v_lshl_add_u64 v[132:133], s[94:95], 1, v[142:143]
	v_cvt_pk_bf16_f32 v134, v134, v135
	v_cvt_pk_bf16_f32 v135, v136, v137
	v_lshl_add_u64 v[142:143], v[138:139], 1, v[132:133]
	v_mov_b32_e32 v240, v134
	v_mov_b32_e32 v241, v135
	v_mov_b32_e32 v242, v130
	v_mov_b32_e32 v243, v131
	s_nop 1
	v_permlane16_swap_b32_e32 v240, v242
	v_permlane16_swap_b32_e32 v241, v243
	v_lshl_add_u64 v[238:239], v[142:143], 0, v[248:249]
	global_store_dwordx4 v[238:239], v[240:243], off
	v_mov_b64_e32 v[132:133], v[28:29]
	v_mov_b64_e32 v[136:137], v[32:33]
	s_and_b64 vcc, exec, s[14:15]
	v_mov_b64_e32 v[130:131], v[26:27]
	v_mov_b64_e32 v[134:135], v[30:31]
	s_cbranch_vccnz .LBB0_932
	s_waitcnt vmcnt(15)
	v_pk_mul_f32 v[134:135], v[28:29], v[208:209]
	v_pk_mul_f32 v[140:141], v[26:27], v[206:207]
	v_pk_mul_f32 v[132:133], v[32:33], v[208:209]
	v_pk_mul_f32 v[130:131], v[30:31], v[206:207]
	v_pk_fma_f32 v[136:137], v[32:33], v[212:213], v[134:135] neg_lo:[0,0,1] neg_hi:[0,0,1]
	v_pk_fma_f32 v[134:135], v[30:31], v[210:211], v[140:141] neg_lo:[0,0,1] neg_hi:[0,0,1]
	v_pk_fma_f32 v[132:133], v[28:29], v[212:213], v[132:133]
	v_pk_fma_f32 v[130:131], v[26:27], v[210:211], v[130:131]
.LBB0_932:
	v_pk_mul_f32 v[136:137], v[136:137], s[80:81] op_sel_hi:[1,0]
	v_pk_mul_f32 v[134:135], v[134:135], s[80:81] op_sel_hi:[1,0]
	v_pk_mul_f32 v[132:133], v[132:133], s[80:81] op_sel_hi:[1,0]
	v_pk_mul_f32 v[130:131], v[130:131], s[80:81] op_sel_hi:[1,0]
	v_cvt_pk_bf16_f32 v134, v134, v135
	v_cvt_pk_bf16_f32 v135, v136, v137
	v_cvt_pk_bf16_f32 v130, v130, v131
	v_cvt_pk_bf16_f32 v131, v132, v133
	v_mov_b32_e32 v244, v134
	v_mov_b32_e32 v245, v135
	v_mov_b32_e32 v246, v130
	v_mov_b32_e32 v247, v131
	s_nop 1
	v_permlane16_swap_b32_e32 v244, v246
	v_permlane16_swap_b32_e32 v245, v247
	v_lshl_add_u64 v[234:235], v[142:143], 0, v[248:249]
	global_store_dwordx4 v[234:235], v[244:247], off offset:256
	v_add_u32_e32 v142, 0x90, v158
	s_movk_i32 s24, 0x7f70
	v_and_b32_e32 v130, 0x7df, v142
	v_cmp_gt_i32_e32 vcc, s24, v158
	v_mov_b64_e32 v[136:137], v[56:57]
	v_mov_b64_e32 v[134:135], v[54:55]
	v_cndmask_b32_e32 v130, v145, v130, vcc
	v_lshlrev_b32_e32 v150, 7, v130
	v_lshl_add_u64 v[130:131], s[68:69], 0, v[150:151]
	v_lshl_add_u64 v[140:141], v[138:139], 2, v[130:131]
	v_mov_b64_e32 v[132:133], v[52:53]
	s_and_b64 vcc, exec, s[12:13]
	v_mov_b64_e32 v[130:131], v[50:51]
	s_cbranch_vccnz .LBB0_934
	s_waitcnt vmcnt(14)
	v_pk_mul_f32 v[134:135], v[52:53], v[216:217]
	v_pk_mul_f32 v[170:171], v[50:51], v[214:215]
	v_pk_mul_f32 v[132:133], v[56:57], v[216:217]
	v_pk_mul_f32 v[130:131], v[54:55], v[214:215]
	v_pk_fma_f32 v[136:137], v[56:57], v[220:221], v[134:135] neg_lo:[0,0,1] neg_hi:[0,0,1]
	v_pk_fma_f32 v[134:135], v[54:55], v[218:219], v[170:171] neg_lo:[0,0,1] neg_hi:[0,0,1]
	v_pk_fma_f32 v[132:133], v[52:53], v[220:221], v[132:133]
	v_pk_fma_f32 v[130:131], v[50:51], v[218:219], v[130:131]
; __device__ __forceinline__ unsigned pk2(float lo, float hi) { f32x2_t v = {lo, hi}; bf16x2_t b = __builtin_convertvector(v, bf16x2_t); return __builtin_bit_cast(unsigned, b); }
;     __device__ __forceinline__ void operator()(const f32x4 (&acc)[2][2][4][2], const Unit& u, int wr, int wc, int fr, int fq) const {
;     ...
;                 for (int m = 0; m < 4; ++m) { const int row = row0 + ai * HALF + m * 16; const float* rp = rope + posidx(row) * 32 + 4 * fq; bf16_t* qp = Q + (size_t)row * QW;
; #pragma unroll
;                     for (int bj = 0; bj < 2; ++bj) { const int col32 = u.pn * BM + bj * HALF + wc * 32; f32x4 v0 = acc[ai][bj][m][0], v1 = acc[ai][bj][m][1];
;                         if ((col32 % 96) == 64) { const f32x4 c = *(const f32x4*)rp, s = *(const f32x4*)(rp + 16); const f32x4 o0 = v0 * c - v1 * s, o1 = v1 * c + v0 * s; v0 = o0; v1 = o1; }
;                         v0 = v0 * QSCALE; v1 = v1 * QSCALE;
;                         u32x2 w0, w1; w0.x = pk2(v0[0], v0[1]); w0.y = pk2(v0[2], v0[3]); w1.x = pk2(v1[0], v1[1]); w1.y = pk2(v1[2], v1[3]);
;                         *(u32x2*)(qp + col32 + 4 * fq) = w0; *(u32x2*)(qp + col32 + 16 + 4 * fq) = w1; } }
.LBB0_934:
	v_mov_b64_e32 v[160:161], s[66:67]
	v_mad_i64_i32 v[142:143], s[24:25], v142, s41, v[160:161]
	v_pk_mul_f32 v[132:133], v[132:133], s[80:81] op_sel_hi:[1,0]
	v_pk_mul_f32 v[130:131], v[130:131], s[80:81] op_sel_hi:[1,0]
	v_pk_mul_f32 v[136:137], v[136:137], s[80:81] op_sel_hi:[1,0]
	v_pk_mul_f32 v[134:135], v[134:135], s[80:81] op_sel_hi:[1,0]
	v_cvt_pk_bf16_f32 v130, v130, v131
	v_cvt_pk_bf16_f32 v131, v132, v133
	v_lshl_add_u64 v[132:133], s[94:95], 1, v[142:143]
	v_cvt_pk_bf16_f32 v134, v134, v135
	v_cvt_pk_bf16_f32 v135, v136, v137
	v_lshl_add_u64 v[142:143], v[138:139], 1, v[132:133]
	v_mov_b32_e32 v226, v134
	v_mov_b32_e32 v227, v135
	v_mov_b32_e32 v228, v130
	v_mov_b32_e32 v229, v131
	s_nop 1
	v_permlane16_swap_b32_e32 v226, v228
	v_permlane16_swap_b32_e32 v227, v229
	v_lshl_add_u64 v[224:225], v[142:143], 0, v[248:249]
	global_store_dwordx4 v[224:225], v[226:229], off
	v_mov_b64_e32 v[132:133], v[20:21]
	v_mov_b64_e32 v[136:137], v[24:25]
	s_and_b64 vcc, exec, s[14:15]
	v_mov_b64_e32 v[130:131], v[18:19]
	v_mov_b64_e32 v[134:135], v[22:23]
	s_cbranch_vccnz .LBB0_936
	s_waitcnt vmcnt(15)
	v_pk_mul_f32 v[134:135], v[20:21], v[216:217]
	v_pk_mul_f32 v[140:141], v[18:19], v[214:215]
	v_pk_mul_f32 v[132:133], v[24:25], v[216:217]
	v_pk_mul_f32 v[130:131], v[22:23], v[214:215]
	v_pk_fma_f32 v[136:137], v[24:25], v[220:221], v[134:135] neg_lo:[0,0,1] neg_hi:[0,0,1]
	v_pk_fma_f32 v[134:135], v[22:23], v[218:219], v[140:141] neg_lo:[0,0,1] neg_hi:[0,0,1]
	v_pk_fma_f32 v[132:133], v[20:21], v[220:221], v[132:133]
	v_pk_fma_f32 v[130:131], v[18:19], v[218:219], v[130:131]
.LBB0_936:
	v_pk_mul_f32 v[136:137], v[136:137], s[80:81] op_sel_hi:[1,0]
	v_pk_mul_f32 v[134:135], v[134:135], s[80:81] op_sel_hi:[1,0]
	v_pk_mul_f32 v[132:133], v[132:133], s[80:81] op_sel_hi:[1,0]
	v_pk_mul_f32 v[130:131], v[130:131], s[80:81] op_sel_hi:[1,0]
	v_cvt_pk_bf16_f32 v134, v134, v135
	v_cvt_pk_bf16_f32 v135, v136, v137
	v_cvt_pk_bf16_f32 v130, v130, v131
	v_cvt_pk_bf16_f32 v131, v132, v133
	v_mov_b32_e32 v230, v134
	v_mov_b32_e32 v231, v135
	v_mov_b32_e32 v232, v130
	v_mov_b32_e32 v233, v131
	s_nop 1
	v_permlane16_swap_b32_e32 v230, v232
	v_permlane16_swap_b32_e32 v231, v233
	v_lshl_add_u64 v[222:223], v[142:143], 0, v[248:249]
	global_store_dwordx4 v[222:223], v[230:233], off offset:256
	v_add_u32_e32 v142, 0xa0, v158
	s_movk_i32 s24, 0x7f60
	v_and_b32_e32 v130, 0x7ef, v142
	v_cmp_gt_i32_e32 vcc, s24, v158
	v_mov_b64_e32 v[136:137], v[48:49]
	v_mov_b64_e32 v[134:135], v[46:47]
	v_cndmask_b32_e32 v130, v145, v130, vcc
	v_lshlrev_b32_e32 v150, 7, v130
	v_lshl_add_u64 v[130:131], s[68:69], 0, v[150:151]
	v_lshl_add_u64 v[140:141], v[138:139], 2, v[130:131]
	v_mov_b64_e32 v[132:133], v[44:45]
	s_and_b64 vcc, exec, s[12:13]
	v_mov_b64_e32 v[130:131], v[42:43]
	s_cbranch_vccnz .LBB0_938
	s_waitcnt vmcnt(12)
	v_pk_mul_f32 v[134:135], v[44:45], v[124:125]
	v_pk_mul_f32 v[170:171], v[42:43], v[122:123]
	v_pk_mul_f32 v[132:133], v[48:49], v[124:125]
	v_pk_mul_f32 v[130:131], v[46:47], v[122:123]
	v_pk_fma_f32 v[136:137], v[48:49], v[128:129], v[134:135] neg_lo:[0,0,1] neg_hi:[0,0,1]
	v_pk_fma_f32 v[134:135], v[46:47], v[126:127], v[170:171] neg_lo:[0,0,1] neg_hi:[0,0,1]
	v_pk_fma_f32 v[132:133], v[44:45], v[128:129], v[132:133]
	v_pk_fma_f32 v[130:131], v[42:43], v[126:127], v[130:131]
; __device__ __forceinline__ unsigned pk2(float lo, float hi) { f32x2_t v = {lo, hi}; bf16x2_t b = __builtin_convertvector(v, bf16x2_t); return __builtin_bit_cast(unsigned, b); }
;     __device__ __forceinline__ void operator()(const f32x4 (&acc)[2][2][4][2], const Unit& u, int wr, int wc, int fr, int fq) const {
;     ...
;                 for (int m = 0; m < 4; ++m) { const int row = row0 + ai * HALF + m * 16; const float* rp = rope + posidx(row) * 32 + 4 * fq; bf16_t* qp = Q + (size_t)row * QW;
; #pragma unroll
;                     for (int bj = 0; bj < 2; ++bj) { const int col32 = u.pn * BM + bj * HALF + wc * 32; f32x4 v0 = acc[ai][bj][m][0], v1 = acc[ai][bj][m][1];
;                         if ((col32 % 96) == 64) { const f32x4 c = *(const f32x4*)rp, s = *(const f32x4*)(rp + 16); const f32x4 o0 = v0 * c - v1 * s, o1 = v1 * c + v0 * s; v0 = o0; v1 = o1; }
;                         v0 = v0 * QSCALE; v1 = v1 * QSCALE;
;                         u32x2 w0, w1; w0.x = pk2(v0[0], v0[1]); w0.y = pk2(v0[2], v0[3]); w1.x = pk2(v1[0], v1[1]); w1.y = pk2(v1[2], v1[3]);
;                         *(u32x2*)(qp + col32 + 4 * fq) = w0; *(u32x2*)(qp + col32 + 16 + 4 * fq) = w1; } }
.LBB0_938:
	v_mov_b64_e32 v[160:161], s[66:67]
	v_mad_i64_i32 v[142:143], s[24:25], v142, s41, v[160:161]
	v_pk_mul_f32 v[132:133], v[132:133], s[80:81] op_sel_hi:[1,0]
	v_pk_mul_f32 v[130:131], v[130:131], s[80:81] op_sel_hi:[1,0]
	v_pk_mul_f32 v[136:137], v[136:137], s[80:81] op_sel_hi:[1,0]
	v_pk_mul_f32 v[134:135], v[134:135], s[80:81] op_sel_hi:[1,0]
	v_cvt_pk_bf16_f32 v130, v130, v131
	v_cvt_pk_bf16_f32 v131, v132, v133
	v_lshl_add_u64 v[132:133], s[94:95], 1, v[142:143]
	v_cvt_pk_bf16_f32 v134, v134, v135
	v_cvt_pk_bf16_f32 v135, v136, v137
	v_lshl_add_u64 v[142:143], v[138:139], 1, v[132:133]
	v_mov_b32_e32 v240, v134
	v_mov_b32_e32 v241, v135
	v_mov_b32_e32 v242, v130
	v_mov_b32_e32 v243, v131
	s_nop 1
	v_permlane16_swap_b32_e32 v240, v242
	v_permlane16_swap_b32_e32 v241, v243
	v_lshl_add_u64 v[238:239], v[142:143], 0, v[248:249]
	global_store_dwordx4 v[238:239], v[240:243], off
	v_mov_b64_e32 v[132:133], v[12:13]
	v_mov_b64_e32 v[136:137], v[16:17]
	s_and_b64 vcc, exec, s[14:15]
	v_mov_b64_e32 v[130:131], v[10:11]
	v_mov_b64_e32 v[134:135], v[14:15]
	s_cbranch_vccnz .LBB0_940
	s_waitcnt vmcnt(13)
	v_pk_mul_f32 v[134:135], v[12:13], v[124:125]
	v_pk_mul_f32 v[140:141], v[10:11], v[122:123]
	v_pk_mul_f32 v[132:133], v[16:17], v[124:125]
	v_pk_mul_f32 v[130:131], v[14:15], v[122:123]
	v_pk_fma_f32 v[136:137], v[16:17], v[128:129], v[134:135] neg_lo:[0,0,1] neg_hi:[0,0,1]
	v_pk_fma_f32 v[134:135], v[14:15], v[126:127], v[140:141] neg_lo:[0,0,1] neg_hi:[0,0,1]
	v_pk_fma_f32 v[132:133], v[12:13], v[128:129], v[132:133]
	v_pk_fma_f32 v[130:131], v[10:11], v[126:127], v[130:131]
.LBB0_940:
	v_pk_mul_f32 v[136:137], v[136:137], s[80:81] op_sel_hi:[1,0]
	v_pk_mul_f32 v[134:135], v[134:135], s[80:81] op_sel_hi:[1,0]
	v_pk_mul_f32 v[132:133], v[132:133], s[80:81] op_sel_hi:[1,0]
	v_pk_mul_f32 v[130:131], v[130:131], s[80:81] op_sel_hi:[1,0]
	v_cvt_pk_bf16_f32 v134, v134, v135
	v_cvt_pk_bf16_f32 v135, v136, v137
	v_cvt_pk_bf16_f32 v130, v130, v131
	v_cvt_pk_bf16_f32 v131, v132, v133
	v_mov_b32_e32 v244, v134
	v_mov_b32_e32 v245, v135
	v_mov_b32_e32 v246, v130
	v_mov_b32_e32 v247, v131
	s_nop 1
	v_permlane16_swap_b32_e32 v244, v246
	v_permlane16_swap_b32_e32 v245, v247
	v_lshl_add_u64 v[234:235], v[142:143], 0, v[248:249]
	global_store_dwordx4 v[234:235], v[244:247], off offset:256
	v_add_u32_e32 v142, 0xb0, v158
	s_movk_i32 s24, 0x7f50
	v_and_b32_e32 v130, 0x7ff, v142
	v_cmp_gt_i32_e32 vcc, s24, v158
	v_mov_b64_e32 v[136:137], v[40:41]
	v_mov_b64_e32 v[134:135], v[38:39]
	v_cndmask_b32_e32 v130, v145, v130, vcc
	v_lshlrev_b32_e32 v150, 7, v130
	v_lshl_add_u64 v[130:131], s[68:69], 0, v[150:151]
	v_lshl_add_u64 v[140:141], v[138:139], 2, v[130:131]
	v_mov_b64_e32 v[132:133], v[36:37]
	s_and_b64 vcc, exec, s[12:13]
	v_mov_b64_e32 v[130:131], v[34:35]
	s_cbranch_vccnz .LBB0_942
	s_waitcnt vmcnt(12)
	v_pk_mul_f32 v[134:135], v[36:37], v[92:93]
	v_pk_mul_f32 v[170:171], v[34:35], v[90:91]
	v_pk_mul_f32 v[132:133], v[40:41], v[92:93]
	v_pk_mul_f32 v[130:131], v[38:39], v[90:91]
	v_pk_fma_f32 v[136:137], v[40:41], v[96:97], v[134:135] neg_lo:[0,0,1] neg_hi:[0,0,1]
	v_pk_fma_f32 v[134:135], v[38:39], v[94:95], v[170:171] neg_lo:[0,0,1] neg_hi:[0,0,1]
	v_pk_fma_f32 v[132:133], v[36:37], v[96:97], v[132:133]
	v_pk_fma_f32 v[130:131], v[34:35], v[94:95], v[130:131]
.LBB0_942:
	v_mov_b64_e32 v[160:161], s[66:67]
	v_mad_i64_i32 v[142:143], s[12:13], v142, s41, v[160:161]
	v_pk_mul_f32 v[132:133], v[132:133], s[80:81] op_sel_hi:[1,0]
	v_pk_mul_f32 v[130:131], v[130:131], s[80:81] op_sel_hi:[1,0]
	v_pk_mul_f32 v[136:137], v[136:137], s[80:81] op_sel_hi:[1,0]
	v_pk_mul_f32 v[134:135], v[134:135], s[80:81] op_sel_hi:[1,0]
	v_cvt_pk_bf16_f32 v130, v130, v131
	v_cvt_pk_bf16_f32 v131, v132, v133
	v_lshl_add_u64 v[132:133], s[94:95], 1, v[142:143]
	v_cvt_pk_bf16_f32 v134, v134, v135
	v_cvt_pk_bf16_f32 v135, v136, v137
	v_lshl_add_u64 v[138:139], v[138:139], 1, v[132:133]
	v_mov_b32_e32 v226, v134
	v_mov_b32_e32 v227, v135
	v_mov_b32_e32 v228, v130
	v_mov_b32_e32 v229, v131
	s_nop 1
	v_permlane16_swap_b32_e32 v226, v228
	v_permlane16_swap_b32_e32 v227, v229
	v_lshl_add_u64 v[224:225], v[138:139], 0, v[248:249]
	global_store_dwordx4 v[224:225], v[226:229], off
	v_mov_b64_e32 v[132:133], v[4:5]
	v_mov_b64_e32 v[136:137], v[8:9]
	s_and_b64 vcc, exec, s[14:15]
	v_mov_b64_e32 v[130:131], v[2:3]
	v_mov_b64_e32 v[134:135], v[6:7]
	s_cbranch_vccnz .LBB0_944
	s_waitcnt vmcnt(13)
	v_pk_mul_f32 v[134:135], v[4:5], v[92:93]
	v_pk_mul_f32 v[160:161], v[2:3], v[90:91]
	v_pk_mul_f32 v[132:133], v[8:9], v[92:93]
	v_pk_mul_f32 v[130:131], v[6:7], v[90:91]
	v_pk_fma_f32 v[136:137], v[8:9], v[96:97], v[134:135] neg_lo:[0,0,1] neg_hi:[0,0,1]
	v_pk_fma_f32 v[134:135], v[6:7], v[94:95], v[160:161] neg_lo:[0,0,1] neg_hi:[0,0,1]
	v_pk_fma_f32 v[132:133], v[4:5], v[96:97], v[132:133]
	v_pk_fma_f32 v[130:131], v[2:3], v[94:95], v[130:131]
